# grid-barrier poll loops (GSYNC 2-6): 16 serialised sc1 counter loads issued in parallel as global loads, one wait
# baseline (speedup 1.0000x reference)
.LBB0_385:
	v_mov_b64_e32 v[12:13], s[38:39]
	s_waitcnt lgkmcnt(0)
	global_load_dword v11, v[12:13], off offset:1024 sc1
	global_load_dword v0, v[12:13], off offset:1280 sc1
	global_load_dword v1, v[12:13], off offset:1536 sc1
	global_load_dword v2, v[12:13], off offset:1792 sc1
	global_load_dword v3, v[12:13], off offset:2048 sc1
	global_load_dword v4, v[12:13], off offset:2304 sc1
	global_load_dword v5, v[12:13], off offset:2560 sc1
	global_load_dword v6, v[12:13], off offset:2816 sc1
	global_load_dword v7, v[12:13], off offset:3072 sc1
	global_load_dword v8, v[12:13], off offset:3328 sc1
	global_load_dword v9, v[12:13], off offset:3584 sc1
	global_load_dword v10, v[12:13], off offset:3840 sc1
	v_mov_b64_e32 v[12:13], s[0:1]
	global_load_dword v12, v[12:13], off sc1
	v_mov_b64_e32 v[14:15], s[4:5]
	global_load_dword v13, v[14:15], off sc1
	v_mov_b64_e32 v[14:15], s[6:7]
	global_load_dword v14, v[14:15], off sc1
	v_mov_b64_e32 v[16:17], s[8:9]
	global_load_dword v15, v[16:17], off sc1
	s_or_b64 s[18:19], s[18:19], exec
	s_or_b64 s[16:17], s[16:17], exec
	s_waitcnt vmcnt(0) lgkmcnt(0)
	v_add_u32_e32 v16, v0, v11
	v_add_u32_e32 v16, v16, v1
	v_add_u32_e32 v16, v16, v2
	v_add_u32_e32 v16, v16, v3
	v_add_u32_e32 v16, v16, v4
	v_add_u32_e32 v16, v16, v5
	v_add_u32_e32 v16, v16, v6
	v_add_u32_e32 v16, v16, v7
	v_add_u32_e32 v16, v16, v8
	v_add_u32_e32 v16, v16, v9
	v_add_u32_e32 v16, v16, v10
	v_add_u32_e32 v16, v16, v12
	v_add_u32_e32 v16, v16, v13
	v_add_u32_e32 v16, v16, v14
	v_add_u32_e32 v16, v16, v15
	v_cmp_ne_u32_e32 vcc, s90, v16
	s_and_saveexec_b64 s[20:21], vcc
	s_cbranch_execz .LBB0_384
	s_and_b32 s24, s30, 0xff
	s_mov_b64 s[22:23], -1
	s_cmp_eq_u32 s24, 0
	s_mov_b64 s[26:27], -1
	s_mov_b64 s[24:25], -1
	s_sleep 1
	s_cbranch_scc1 .LBB0_388
	s_and_saveexec_b64 s[28:29], s[26:27]
	s_cbranch_execz .LBB0_383
	s_branch .LBB0_391

.LBB0_754:
	v_mov_b64_e32 v[12:13], s[40:41]
	s_waitcnt lgkmcnt(0)
	global_load_dword v11, v[12:13], off offset:1024 sc1
	global_load_dword v0, v[12:13], off offset:1280 sc1
	global_load_dword v1, v[12:13], off offset:1536 sc1
	global_load_dword v2, v[12:13], off offset:1792 sc1
	global_load_dword v3, v[12:13], off offset:2048 sc1
	global_load_dword v4, v[12:13], off offset:2304 sc1
	global_load_dword v5, v[12:13], off offset:2560 sc1
	global_load_dword v6, v[12:13], off offset:2816 sc1
	global_load_dword v7, v[12:13], off offset:3072 sc1
	global_load_dword v8, v[12:13], off offset:3328 sc1
	global_load_dword v9, v[12:13], off offset:3584 sc1
	global_load_dword v10, v[12:13], off offset:3840 sc1
	v_mov_b64_e32 v[12:13], s[0:1]
	global_load_dword v12, v[12:13], off sc1
	v_mov_b64_e32 v[14:15], s[4:5]
	global_load_dword v13, v[14:15], off sc1
	v_mov_b64_e32 v[14:15], s[8:9]
	global_load_dword v14, v[14:15], off sc1
	v_mov_b64_e32 v[16:17], s[10:11]
	global_load_dword v15, v[16:17], off sc1
	s_or_b64 s[20:21], s[20:21], exec
	s_or_b64 s[18:19], s[18:19], exec
	s_waitcnt vmcnt(0) lgkmcnt(0)
	v_add_u32_e32 v16, v0, v11
	v_add_u32_e32 v16, v16, v1
	v_add_u32_e32 v16, v16, v2
	v_add_u32_e32 v16, v16, v3
	v_add_u32_e32 v16, v16, v4
	v_add_u32_e32 v16, v16, v5
	v_add_u32_e32 v16, v16, v6
	v_add_u32_e32 v16, v16, v7
	v_add_u32_e32 v16, v16, v8
	v_add_u32_e32 v16, v16, v9
	v_add_u32_e32 v16, v16, v10
	v_add_u32_e32 v16, v16, v12
	v_add_u32_e32 v16, v16, v13
	v_add_u32_e32 v16, v16, v14
	v_add_u32_e32 v16, v16, v15
	v_cmp_ne_u32_e32 vcc, s90, v16
	s_and_saveexec_b64 s[22:23], vcc
	s_cbranch_execz .LBB0_753
	s_and_b32 s26, s33, 0xff
	s_mov_b64 s[24:25], -1
	s_cmp_eq_u32 s26, 0
	s_mov_b64 s[28:29], -1
	s_mov_b64 s[26:27], -1
	s_sleep 1
	s_cbranch_scc1 .LBB0_757
	s_and_saveexec_b64 s[30:31], s[28:29]
	s_cbranch_execz .LBB0_752
	s_branch .LBB0_760
